# v26 + spatial phase: u-tile loads prefetched before the MFMA section
# speedup vs baseline: 1.0277x; 1.0035x over previous
; #define LAS __attribute__((address_space(3)))
; __device__ __forceinline__ unsigned cvt_pk_bf16(float lo, float hi) { f32x2 v = {lo, hi}; bf16x2_t b = __builtin_convertvector(v, bf16x2_t); return __builtin_bit_cast(unsigned, b); }
; __device__ __forceinline__ float bf_lo(unsigned u) { return __uint_as_float(u << 16); }
; __device__ __forceinline__ float bf_hi(unsigned u) { return __uint_as_float(u & 0xffff0000u); }
; __device__ __forceinline__ int launder_s(int v) { asm volatile("" : "+s"(v)); return v; }
; __device__ __forceinline__ void phase_spatial(const Args& a, LAS unsigned char* lds, int j, int nchunks) {
;     ...
;     for (int idx = launder_s(blockIdx.x); idx < nchunks * 8; idx += G) {
;         const int chunk = idx >> 3, g = idx & 7; const size_t row0 = (size_t)chunk * 128;
;         if (g != gcur) {
; #pragma unroll
;             for (int p = 0; p < 4; ++p) { const int i = tid + 512 * p; const int row = i >> 4, ch = i & 15; const u32x4 w = *(const u32x4*)(wsb + (size_t)g * 16384 + row * 128 + ch * 8);
;                 *(LAS u32x4*)(wl + row * 256 + ((ch ^ (row & 15)) << 4)) = w; }
;             gcur = g;
;         }
;         {
;             f32x4 g0 = *(const f32x4*)(lng + g * 256 + lch * 8), g1 = *(const f32x4*)(lng + g * 256 + lch * 8 + 4), b0 = *(const f32x4*)(lnb + g * 256 + lch * 8), b1 = *(const f32x4*)(lnb + g * 256 + lch * 8 + 4);
; #pragma unroll
;             for (int p = 0; p < 8; ++p) { const int row = lrow + 16 * p; const u32x4 w = *(const u32x4*)(Z + (row0 + row) * SGUW + SGUH + g * 256 + lch * 8);
;                 const f32x2 ms = *(const f32x2*)(st + 2 * (row0 + row));
;                 f32x4 x0 = {bf_lo(w.x), bf_hi(w.x), bf_lo(w.y), bf_hi(w.y)}, x1 = {bf_lo(w.z), bf_hi(w.z), bf_lo(w.w), bf_hi(w.w)};
;                 x0 = (x0 - ms.x) * ms.y * g0 + b0; x1 = (x1 - ms.x) * ms.y * g1 + b1;
;                 u32x4 o; o.x = cvt_pk_bf16(x0[0], x0[1]); o.y = cvt_pk_bf16(x0[2], x0[3]); o.z = cvt_pk_bf16(x1[0], x1[1]); o.w = cvt_pk_bf16(x1[2], x1[3]);
;                 *(LAS u32x4*)(vt + (lch >> 2) * 8192 + (row >> 3) * 512 + (row & 7) * 64 + (lch & 3) * 16) = o; }
.LBB0_251:
	s_ashr_i32 s12, s8, 3
	s_ashr_i32 s13, s12, 31
	s_lshl_b64 s[12:13], s[12:13], 7
	v_lshl_add_u64 v[196:197], s[12:13], 0, v[66:67]
	s_lshl_b32 s0, s10, 10
	v_lshlrev_b64 v[98:99], 13, v[196:197]
	v_lshl_add_u64 v[6:7], v[70:71], 0, s[0:1]
	v_lshl_add_u64 v[14:15], v[72:73], 0, s[0:1]
	v_lshl_add_u64 v[156:157], s[46:47], 0, v[98:99]
	s_lshl_b32 s0, s10, 9
	v_lshl_add_u64 v[156:157], v[156:157], 0, s[0:1]
	v_lshl_add_u64 v[156:157], v[156:157], 0, v[0:1]
	s_movk_i32 s10, 0x1000
	v_add_co_u32_e32 v156, vcc, s10, v156
	global_load_dwordx4 v[2:5], v[6:7], off offset:16
	global_load_dwordx4 v[10:13], v[6:7], off
	v_addc_co_u32_e32 v157, vcc, 0, v157, vcc
	global_load_dwordx4 v[6:9], v[14:15], off offset:16
	s_nop 0
	global_load_dwordx4 v[14:17], v[14:15], off
	v_lshl_add_u64 v[196:197], v[196:197], 3, s[50:51]
	global_load_dwordx4 v[156:159], v[156:157], off
	v_lshl_or_b32 v147, v114, 2, s0
	global_load_dwordx2 v[196:197], v[196:197], off
	s_add_i32 s8, s8, s3
	s_cmp_ge_i32 s8, s2
	v_lshl_add_u64 v[198:199], s[12:13], 0, v[84:85]
	v_lshlrev_b64 v[100:101], 13, v[198:199]
	v_lshl_add_u64 v[160:161], s[46:47], 0, v[100:101]
	v_lshl_add_u64 v[160:161], v[160:161], 0, s[0:1]
	v_lshl_add_u64 v[160:161], v[160:161], 0, v[0:1]
	v_add_co_u32_e32 v160, vcc, s10, v160
	v_lshl_add_u64 v[198:199], v[198:199], 3, s[50:51]
	s_nop 0
	v_addc_co_u32_e32 v161, vcc, 0, v161, vcc
	global_load_dwordx4 v[160:163], v[160:161], off
	s_nop 0
	global_load_dwordx2 v[198:199], v[198:199], off
	v_lshl_add_u64 v[200:201], s[12:13], 0, v[86:87]
	v_lshlrev_b64 v[102:103], 13, v[200:201]
	v_lshl_add_u64 v[164:165], s[46:47], 0, v[102:103]
	v_lshl_add_u64 v[164:165], v[164:165], 0, s[0:1]
	v_lshl_add_u64 v[164:165], v[164:165], 0, v[0:1]
	v_add_co_u32_e32 v164, vcc, s10, v164
	v_lshl_add_u64 v[200:201], v[200:201], 3, s[50:51]
	s_nop 0
	v_addc_co_u32_e32 v165, vcc, 0, v165, vcc
	global_load_dwordx4 v[164:167], v[164:165], off
	s_nop 0
	global_load_dwordx2 v[200:201], v[200:201], off
	v_lshl_add_u64 v[202:203], s[12:13], 0, v[88:89]
	v_lshlrev_b64 v[104:105], 13, v[202:203]
	v_lshl_add_u64 v[168:169], s[46:47], 0, v[104:105]
	v_lshl_add_u64 v[168:169], v[168:169], 0, s[0:1]
	v_lshl_add_u64 v[168:169], v[168:169], 0, v[0:1]
	v_add_co_u32_e32 v168, vcc, s10, v168
	v_lshl_add_u64 v[202:203], v[202:203], 3, s[50:51]
	s_nop 0
	v_addc_co_u32_e32 v169, vcc, 0, v169, vcc
	global_load_dwordx4 v[168:171], v[168:169], off
	s_nop 0
	global_load_dwordx2 v[202:203], v[202:203], off
	v_lshl_add_u64 v[208:209], s[12:13], 0, v[90:91]
	v_lshlrev_b64 v[106:107], 13, v[208:209]
	v_lshl_add_u64 v[172:173], s[46:47], 0, v[106:107]
	v_lshl_add_u64 v[172:173], v[172:173], 0, s[0:1]
	v_lshl_add_u64 v[172:173], v[172:173], 0, v[0:1]
	v_add_co_u32_e32 v172, vcc, s10, v172
	v_lshl_add_u64 v[208:209], v[208:209], 3, s[50:51]
	s_nop 0
	v_addc_co_u32_e32 v173, vcc, 0, v173, vcc
	global_load_dwordx4 v[172:175], v[172:173], off
	s_nop 0
	global_load_dwordx2 v[208:209], v[208:209], off
	v_lshl_add_u64 v[210:211], s[12:13], 0, v[92:93]
	v_lshlrev_b64 v[108:109], 13, v[210:211]
	v_lshl_add_u64 v[184:185], s[46:47], 0, v[108:109]
	v_lshl_add_u64 v[184:185], v[184:185], 0, s[0:1]
	v_lshl_add_u64 v[184:185], v[184:185], 0, v[0:1]
	v_add_co_u32_e32 v184, vcc, s10, v184
	v_lshl_add_u64 v[210:211], v[210:211], 3, s[50:51]
	s_nop 0
	v_addc_co_u32_e32 v185, vcc, 0, v185, vcc
	global_load_dwordx4 v[184:187], v[184:185], off
	s_nop 0
	global_load_dwordx2 v[210:211], v[210:211], off
	v_lshl_add_u64 v[212:213], s[12:13], 0, v[94:95]
	v_lshlrev_b64 v[110:111], 13, v[212:213]
	v_lshl_add_u64 v[188:189], s[46:47], 0, v[110:111]
	v_lshl_add_u64 v[188:189], v[188:189], 0, s[0:1]
	v_lshl_add_u64 v[188:189], v[188:189], 0, v[0:1]
	v_add_co_u32_e32 v188, vcc, s10, v188
	v_lshl_add_u64 v[212:213], v[212:213], 3, s[50:51]
	s_nop 0
	v_addc_co_u32_e32 v189, vcc, 0, v189, vcc
	global_load_dwordx4 v[188:191], v[188:189], off
	s_nop 0
	global_load_dwordx2 v[212:213], v[212:213], off
	v_lshl_add_u64 v[22:23], s[12:13], 0, v[96:97]
	v_lshlrev_b64 v[112:113], 13, v[22:23]
	v_lshl_add_u64 v[18:19], s[46:47], 0, v[112:113]
	v_lshl_add_u64 v[18:19], v[18:19], 0, s[0:1]
	v_lshl_add_u64 v[18:19], v[18:19], 0, v[0:1]
	v_add_co_u32_e32 v18, vcc, s10, v18
	v_lshl_add_u64 v[22:23], v[22:23], 3, s[50:51]
	s_nop 0
	v_addc_co_u32_e32 v19, vcc, 0, v19, vcc
	global_load_dwordx4 v[18:21], v[18:19], off
	s_nop 0
	global_load_dwordx2 v[22:23], v[22:23], off
	global_load_dword v224, v147, s[6:7]
	global_load_dword v225, v147, s[6:7] offset:128
	global_load_dword v226, v147, s[6:7] offset:256
	global_load_dword v227, v147, s[6:7] offset:384
	s_waitcnt vmcnt(18)
	v_lshlrev_b32_e32 v24, 16, v156
	v_and_b32_e32 v25, 0xffff0000, v156
	v_lshlrev_b32_e32 v156, 16, v157
	v_and_b32_e32 v157, 0xffff0000, v157
	v_lshlrev_b32_e32 v26, 16, v158
	v_and_b32_e32 v27, 0xffff0000, v158
	v_lshlrev_b32_e32 v28, 16, v159
	v_and_b32_e32 v29, 0xffff0000, v159
	v_sub_f32_e32 v157, v157, v196
	v_sub_f32_e32 v156, v156, v196
	v_sub_f32_e32 v159, v25, v196
	v_sub_f32_e32 v158, v24, v196
	v_pk_mul_f32 v[158:159], v[196:197], v[158:159] op_sel:[1,0]
	v_pk_mul_f32 v[156:157], v[196:197], v[156:157] op_sel:[1,0]
	v_sub_f32_e32 v27, v27, v196
	v_pk_fma_f32 v[24:25], v[12:13], v[156:157], v[16:17]
	v_pk_fma_f32 v[156:157], v[10:11], v[158:159], v[14:15]
	v_sub_f32_e32 v159, v29, v196
	v_sub_f32_e32 v158, v28, v196
	v_sub_f32_e32 v26, v26, v196
	v_pk_mul_f32 v[26:27], v[196:197], v[26:27] op_sel:[1,0]
	v_pk_mul_f32 v[158:159], v[196:197], v[158:159] op_sel:[1,0]
	v_cvt_pk_bf16_f32 v156, v156, v157
	v_pk_fma_f32 v[196:197], v[4:5], v[158:159], v[8:9]
	v_pk_fma_f32 v[158:159], v[2:3], v[26:27], v[6:7]
	v_cvt_pk_bf16_f32 v157, v24, v25
	v_cvt_pk_bf16_f32 v158, v158, v159
	v_cvt_pk_bf16_f32 v159, v196, v197
	ds_write_b128 v121, v[156:159]
	s_waitcnt vmcnt(16)
; #define LAS __attribute__((address_space(3)))
; __device__ __forceinline__ unsigned cvt_pk_bf16(float lo, float hi) { f32x2 v = {lo, hi}; bf16x2_t b = __builtin_convertvector(v, bf16x2_t); return __builtin_bit_cast(unsigned, b); }
; __device__ __forceinline__ float bf_lo(unsigned u) { return __uint_as_float(u << 16); }
; __device__ __forceinline__ float bf_hi(unsigned u) { return __uint_as_float(u & 0xffff0000u); }
; __device__ __forceinline__ void phase_spatial(const Args& a, LAS unsigned char* lds, int j, int nchunks) {
;     ...
;             f32x4 g0 = *(const f32x4*)(lng + g * 256 + lch * 8), g1 = *(const f32x4*)(lng + g * 256 + lch * 8 + 4), b0 = *(const f32x4*)(lnb + g * 256 + lch * 8), b1 = *(const f32x4*)(lnb + g * 256 + lch * 8 + 4);
; #pragma unroll
;             for (int p = 0; p < 8; ++p) { const int row = lrow + 16 * p; const u32x4 w = *(const u32x4*)(Z + (row0 + row) * SGUW + SGUH + g * 256 + lch * 8);
;                 const f32x2 ms = *(const f32x2*)(st + 2 * (row0 + row));
;                 f32x4 x0 = {bf_lo(w.x), bf_hi(w.x), bf_lo(w.y), bf_hi(w.y)}, x1 = {bf_lo(w.z), bf_hi(w.z), bf_lo(w.w), bf_hi(w.w)};
;                 x0 = (x0 - ms.x) * ms.y * g0 + b0; x1 = (x1 - ms.x) * ms.y * g1 + b1;
;                 u32x4 o; o.x = cvt_pk_bf16(x0[0], x0[1]); o.y = cvt_pk_bf16(x0[2], x0[3]); o.z = cvt_pk_bf16(x1[0], x1[1]); o.w = cvt_pk_bf16(x1[2], x1[3]);
;                 *(LAS u32x4*)(vt + (lch >> 2) * 8192 + (row >> 3) * 512 + (row & 7) * 64 + (lch & 3) * 16) = o; }
	v_lshlrev_b32_e32 v24, 16, v160
	v_and_b32_e32 v25, 0xffff0000, v160
	v_lshlrev_b32_e32 v160, 16, v161
	v_and_b32_e32 v161, 0xffff0000, v161
	v_lshlrev_b32_e32 v26, 16, v162
	v_and_b32_e32 v27, 0xffff0000, v162
	v_lshlrev_b32_e32 v28, 16, v163
	v_and_b32_e32 v29, 0xffff0000, v163
	v_sub_f32_e32 v161, v161, v198
	v_sub_f32_e32 v160, v160, v198
	v_sub_f32_e32 v163, v25, v198
	v_sub_f32_e32 v162, v24, v198
	v_pk_mul_f32 v[162:163], v[198:199], v[162:163] op_sel:[1,0]
	v_pk_mul_f32 v[160:161], v[198:199], v[160:161] op_sel:[1,0]
	v_sub_f32_e32 v27, v27, v198
	v_pk_fma_f32 v[24:25], v[12:13], v[160:161], v[16:17]
	v_pk_fma_f32 v[160:161], v[10:11], v[162:163], v[14:15]
	v_sub_f32_e32 v163, v29, v198
	v_sub_f32_e32 v162, v28, v198
	v_sub_f32_e32 v26, v26, v198
	v_pk_mul_f32 v[26:27], v[198:199], v[26:27] op_sel:[1,0]
	v_pk_mul_f32 v[162:163], v[198:199], v[162:163] op_sel:[1,0]
	v_cvt_pk_bf16_f32 v160, v160, v161
	v_pk_fma_f32 v[198:199], v[4:5], v[162:163], v[8:9]
	v_pk_fma_f32 v[162:163], v[2:3], v[26:27], v[6:7]
	v_cvt_pk_bf16_f32 v161, v24, v25
	v_cvt_pk_bf16_f32 v162, v162, v163
	v_cvt_pk_bf16_f32 v163, v198, v199
	ds_write_b128 v122, v[160:163]
	s_waitcnt vmcnt(14)
	v_lshlrev_b32_e32 v24, 16, v164
	v_and_b32_e32 v25, 0xffff0000, v164
	v_lshlrev_b32_e32 v164, 16, v165
	v_and_b32_e32 v165, 0xffff0000, v165
	v_lshlrev_b32_e32 v26, 16, v166
	v_and_b32_e32 v27, 0xffff0000, v166
	v_lshlrev_b32_e32 v28, 16, v167
	v_and_b32_e32 v29, 0xffff0000, v167
	v_sub_f32_e32 v165, v165, v200
	v_sub_f32_e32 v164, v164, v200
	v_sub_f32_e32 v167, v25, v200
	v_sub_f32_e32 v166, v24, v200
	v_pk_mul_f32 v[166:167], v[200:201], v[166:167] op_sel:[1,0]
	v_pk_mul_f32 v[164:165], v[200:201], v[164:165] op_sel:[1,0]
	v_sub_f32_e32 v27, v27, v200
	v_pk_fma_f32 v[24:25], v[12:13], v[164:165], v[16:17]
	v_pk_fma_f32 v[164:165], v[10:11], v[166:167], v[14:15]
	v_sub_f32_e32 v167, v29, v200
	v_sub_f32_e32 v166, v28, v200
	v_sub_f32_e32 v26, v26, v200
	v_pk_mul_f32 v[26:27], v[200:201], v[26:27] op_sel:[1,0]
	v_pk_mul_f32 v[166:167], v[200:201], v[166:167] op_sel:[1,0]
	v_cvt_pk_bf16_f32 v164, v164, v165
	v_pk_fma_f32 v[200:201], v[4:5], v[166:167], v[8:9]
	v_pk_fma_f32 v[166:167], v[2:3], v[26:27], v[6:7]
	v_cvt_pk_bf16_f32 v165, v24, v25
	v_cvt_pk_bf16_f32 v166, v166, v167
	v_cvt_pk_bf16_f32 v167, v200, v201
	ds_write_b128 v123, v[164:167]
	s_waitcnt vmcnt(12)
	v_lshlrev_b32_e32 v24, 16, v168
	v_and_b32_e32 v25, 0xffff0000, v168
	v_lshlrev_b32_e32 v168, 16, v169
	v_and_b32_e32 v169, 0xffff0000, v169
	v_lshlrev_b32_e32 v26, 16, v170
	v_and_b32_e32 v27, 0xffff0000, v170
	v_lshlrev_b32_e32 v28, 16, v171
	v_and_b32_e32 v29, 0xffff0000, v171
	v_sub_f32_e32 v169, v169, v202
	v_sub_f32_e32 v168, v168, v202
	v_sub_f32_e32 v171, v25, v202
	v_sub_f32_e32 v170, v24, v202
	v_pk_mul_f32 v[170:171], v[202:203], v[170:171] op_sel:[1,0]
	v_pk_mul_f32 v[168:169], v[202:203], v[168:169] op_sel:[1,0]
	v_sub_f32_e32 v27, v27, v202
	v_pk_fma_f32 v[24:25], v[12:13], v[168:169], v[16:17]
	v_pk_fma_f32 v[168:169], v[10:11], v[170:171], v[14:15]
	v_sub_f32_e32 v171, v29, v202
	v_sub_f32_e32 v170, v28, v202
	v_sub_f32_e32 v26, v26, v202
	v_pk_mul_f32 v[26:27], v[202:203], v[26:27] op_sel:[1,0]
	v_pk_mul_f32 v[170:171], v[202:203], v[170:171] op_sel:[1,0]
	v_cvt_pk_bf16_f32 v168, v168, v169
	v_pk_fma_f32 v[202:203], v[4:5], v[170:171], v[8:9]
	v_pk_fma_f32 v[170:171], v[2:3], v[26:27], v[6:7]
	v_cvt_pk_bf16_f32 v169, v24, v25
	v_cvt_pk_bf16_f32 v170, v170, v171
	v_cvt_pk_bf16_f32 v171, v202, v203
	ds_write_b128 v124, v[168:171]
	s_waitcnt vmcnt(10)
	v_lshlrev_b32_e32 v24, 16, v172
	v_and_b32_e32 v25, 0xffff0000, v172
	v_lshlrev_b32_e32 v172, 16, v173
	v_and_b32_e32 v173, 0xffff0000, v173
	v_lshlrev_b32_e32 v26, 16, v174
	v_and_b32_e32 v27, 0xffff0000, v174
	v_lshlrev_b32_e32 v28, 16, v175
	v_and_b32_e32 v29, 0xffff0000, v175
	v_sub_f32_e32 v173, v173, v208
	v_sub_f32_e32 v172, v172, v208
	v_sub_f32_e32 v175, v25, v208
	v_sub_f32_e32 v174, v24, v208
	v_pk_mul_f32 v[174:175], v[208:209], v[174:175] op_sel:[1,0]
	v_pk_mul_f32 v[172:173], v[208:209], v[172:173] op_sel:[1,0]
	v_sub_f32_e32 v27, v27, v208
	v_pk_fma_f32 v[24:25], v[12:13], v[172:173], v[16:17]
	v_pk_fma_f32 v[172:173], v[10:11], v[174:175], v[14:15]
	v_sub_f32_e32 v175, v29, v208
	v_sub_f32_e32 v174, v28, v208
	v_sub_f32_e32 v26, v26, v208
	v_pk_mul_f32 v[26:27], v[208:209], v[26:27] op_sel:[1,0]
	v_pk_mul_f32 v[174:175], v[208:209], v[174:175] op_sel:[1,0]
	v_cvt_pk_bf16_f32 v172, v172, v173
	v_pk_fma_f32 v[208:209], v[4:5], v[174:175], v[8:9]
	v_pk_fma_f32 v[174:175], v[2:3], v[26:27], v[6:7]
	v_cvt_pk_bf16_f32 v173, v24, v25
	v_cvt_pk_bf16_f32 v174, v174, v175
	v_cvt_pk_bf16_f32 v175, v208, v209
	ds_write_b128 v125, v[172:175]
	s_waitcnt vmcnt(8)
	v_lshlrev_b32_e32 v24, 16, v184
	v_and_b32_e32 v25, 0xffff0000, v184
	v_lshlrev_b32_e32 v184, 16, v185
	v_and_b32_e32 v185, 0xffff0000, v185
	v_lshlrev_b32_e32 v26, 16, v186
	v_and_b32_e32 v27, 0xffff0000, v186
	v_lshlrev_b32_e32 v28, 16, v187
	v_and_b32_e32 v29, 0xffff0000, v187
	v_sub_f32_e32 v185, v185, v210
	v_sub_f32_e32 v184, v184, v210
	v_sub_f32_e32 v187, v25, v210
	v_sub_f32_e32 v186, v24, v210
	v_pk_mul_f32 v[186:187], v[210:211], v[186:187] op_sel:[1,0]
	v_pk_mul_f32 v[184:185], v[210:211], v[184:185] op_sel:[1,0]
	v_sub_f32_e32 v27, v27, v210
	v_pk_fma_f32 v[24:25], v[12:13], v[184:185], v[16:17]
	v_pk_fma_f32 v[184:185], v[10:11], v[186:187], v[14:15]
	v_sub_f32_e32 v187, v29, v210
	v_sub_f32_e32 v186, v28, v210
	v_sub_f32_e32 v26, v26, v210
	v_pk_mul_f32 v[26:27], v[210:211], v[26:27] op_sel:[1,0]
	v_pk_mul_f32 v[186:187], v[210:211], v[186:187] op_sel:[1,0]
	v_cvt_pk_bf16_f32 v184, v184, v185
	v_pk_fma_f32 v[210:211], v[4:5], v[186:187], v[8:9]
	v_pk_fma_f32 v[186:187], v[2:3], v[26:27], v[6:7]
	v_cvt_pk_bf16_f32 v185, v24, v25
	v_cvt_pk_bf16_f32 v186, v186, v187
	v_cvt_pk_bf16_f32 v187, v210, v211
	ds_write_b128 v126, v[184:187]
	s_waitcnt vmcnt(6)
; #define LAS __attribute__((address_space(3)))
; __device__ __forceinline__ unsigned cvt_pk_bf16(float lo, float hi) { f32x2 v = {lo, hi}; bf16x2_t b = __builtin_convertvector(v, bf16x2_t); return __builtin_bit_cast(unsigned, b); }
; __device__ __forceinline__ float bf_lo(unsigned u) { return __uint_as_float(u << 16); }
; __device__ __forceinline__ void phase_spatial(const Args& a, LAS unsigned char* lds, int j, int nchunks) {
;     ...
;             for (int p = 0; p < 8; ++p) { const int row = lrow + 16 * p; const u32x4 w = *(const u32x4*)(Z + (row0 + row) * SGUW + SGUH + g * 256 + lch * 8);
;                 const f32x2 ms = *(const f32x2*)(st + 2 * (row0 + row));
;                 f32x4 x0 = {bf_lo(w.x), bf_hi(w.x), bf_lo(w.y), bf_hi(w.y)}, x1 = {bf_lo(w.z), bf_hi(w.z), bf_lo(w.w), bf_hi(w.w)};
;                 x0 = (x0 - ms.x) * ms.y * g0 + b0; x1 = (x1 - ms.x) * ms.y * g1 + b1;
;                 u32x4 o; o.x = cvt_pk_bf16(x0[0], x0[1]); o.y = cvt_pk_bf16(x0[2], x0[3]); o.z = cvt_pk_bf16(x1[0], x1[1]); o.w = cvt_pk_bf16(x1[2], x1[3]);
;                 *(LAS u32x4*)(vt + (lch >> 2) * 8192 + (row >> 3) * 512 + (row & 7) * 64 + (lch & 3) * 16) = o; }
;         }
;         __syncthreads();
;         f32x16 acc[4];
; #pragma unroll
;         for (int pb = 0; pb < 4; ++pb)
; #pragma unroll
;             for (int i = 0; i < 16; ++i) acc[pb][i] = 0.f;
;         const int vb = wid * 8192 + ((lane >> 4) & 1) * 32 + (lane & 3) * 8 + ((lane & 15) >> 2) * 64;
; #pragma unroll
;         for (int ks = 0; ks < 8; ++ks) {
;             const s16x4 lo = __builtin_bit_cast(s16x4, __builtin_amdgcn_ds_read_tr16_b64_v4i16((LAS s16x4*)(vt + vb + (2 * ks + hi) * 512)));
;             const s16x4 hh = __builtin_bit_cast(s16x4, __builtin_amdgcn_ds_read_tr16_b64_v4i16((LAS s16x4*)(vt + vb + (2 * ks + hi) * 512 + 256)));
;             const bf16x8 vf = __builtin_shufflevector(lo, hh, 0, 1, 2, 3, 4, 5, 6, 7);
; #pragma unroll
;             for (int pb = 0; pb < 4; ++pb) { const int row = 32 * pb + r32; const bf16x8 wf = *(const LAS bf16x8*)(wl + row * 256 + (((2 * ks + hi) ^ (row & 15)) << 4));
;                 acc[pb] = __builtin_amdgcn_mfma_f32_32x32x16_bf16(vf, wf, acc[pb], 0, 0, 0); }
;     ...
;         { u32x4 uu[8];
; #pragma unroll
;           for (int p8 = 0; p8 < 8; ++p8) { const int row = lrow + 16 * p8; uu[p8] = *(const u32x4*)(Z + (row0 + row) * SGUW + g * 256 + lch * 8); }
	v_lshlrev_b32_e32 v24, 16, v188
	v_and_b32_e32 v25, 0xffff0000, v188
	v_lshlrev_b32_e32 v188, 16, v189
	v_and_b32_e32 v189, 0xffff0000, v189
	v_lshlrev_b32_e32 v26, 16, v190
	v_and_b32_e32 v27, 0xffff0000, v190
	v_lshlrev_b32_e32 v28, 16, v191
	v_and_b32_e32 v29, 0xffff0000, v191
	v_sub_f32_e32 v189, v189, v212
	v_sub_f32_e32 v188, v188, v212
	v_sub_f32_e32 v191, v25, v212
	v_sub_f32_e32 v190, v24, v212
	v_pk_mul_f32 v[190:191], v[212:213], v[190:191] op_sel:[1,0]
	v_pk_mul_f32 v[188:189], v[212:213], v[188:189] op_sel:[1,0]
	v_sub_f32_e32 v27, v27, v212
	v_pk_fma_f32 v[24:25], v[12:13], v[188:189], v[16:17]
	v_pk_fma_f32 v[188:189], v[10:11], v[190:191], v[14:15]
	v_sub_f32_e32 v191, v29, v212
	v_sub_f32_e32 v190, v28, v212
	v_sub_f32_e32 v26, v26, v212
	v_pk_mul_f32 v[26:27], v[212:213], v[26:27] op_sel:[1,0]
	v_pk_mul_f32 v[190:191], v[212:213], v[190:191] op_sel:[1,0]
	v_cvt_pk_bf16_f32 v188, v188, v189
	v_pk_fma_f32 v[212:213], v[4:5], v[190:191], v[8:9]
	v_pk_fma_f32 v[190:191], v[2:3], v[26:27], v[6:7]
	v_cvt_pk_bf16_f32 v189, v24, v25
	v_cvt_pk_bf16_f32 v190, v190, v191
	v_cvt_pk_bf16_f32 v191, v212, v213
	ds_write_b128 v127, v[188:191]
	s_waitcnt vmcnt(4)
	v_lshlrev_b32_e32 v24, 16, v18
	v_and_b32_e32 v25, 0xffff0000, v18
	v_lshlrev_b32_e32 v18, 16, v19
	v_and_b32_e32 v19, 0xffff0000, v19
	v_lshlrev_b32_e32 v26, 16, v20
	v_and_b32_e32 v27, 0xffff0000, v20
	v_lshlrev_b32_e32 v28, 16, v21
	v_and_b32_e32 v29, 0xffff0000, v21
	v_sub_f32_e32 v19, v19, v22
	v_sub_f32_e32 v18, v18, v22
	v_sub_f32_e32 v21, v25, v22
	v_sub_f32_e32 v20, v24, v22
	v_pk_mul_f32 v[20:21], v[22:23], v[20:21] op_sel:[1,0]
	v_pk_mul_f32 v[18:19], v[22:23], v[18:19] op_sel:[1,0]
	v_pk_fma_f32 v[10:11], v[10:11], v[20:21], v[14:15]
	v_pk_fma_f32 v[12:13], v[12:13], v[18:19], v[16:17]
	v_sub_f32_e32 v15, v29, v22
	v_sub_f32_e32 v14, v28, v22
	v_sub_f32_e32 v17, v27, v22
	v_sub_f32_e32 v16, v26, v22
	v_pk_mul_f32 v[16:17], v[22:23], v[16:17] op_sel:[1,0]
	v_pk_mul_f32 v[14:15], v[22:23], v[14:15] op_sel:[1,0]
	s_nop 0
	v_pk_fma_f32 v[8:9], v[4:5], v[14:15], v[8:9]
	v_pk_fma_f32 v[4:5], v[2:3], v[16:17], v[6:7]
	v_cvt_pk_bf16_f32 v2, v10, v11
	v_cvt_pk_bf16_f32 v3, v12, v13
	v_cvt_pk_bf16_f32 v4, v4, v5
	v_cvt_pk_bf16_f32 v5, v8, v9
	ds_write_b128 v128, v[2:5]
	v_lshl_add_u64 v[248:249], v[74:75], 0, s[0:1]
	v_lshl_add_u64 v[250:251], v[248:249], 0, v[98:99]
	global_load_dwordx4 v[156:159], v[250:251], off
	v_lshl_add_u64 v[250:251], v[248:249], 0, v[100:101]
	global_load_dwordx4 v[160:163], v[250:251], off
	v_lshl_add_u64 v[250:251], v[248:249], 0, v[102:103]
	global_load_dwordx4 v[208:211], v[250:251], off
	v_lshl_add_u64 v[250:251], v[248:249], 0, v[104:105]
	global_load_dwordx4 v[228:231], v[250:251], off
	v_lshl_add_u64 v[250:251], v[248:249], 0, v[106:107]
	global_load_dwordx4 v[232:235], v[250:251], off
	v_lshl_add_u64 v[250:251], v[248:249], 0, v[108:109]
	global_load_dwordx4 v[236:239], v[250:251], off
	v_lshl_add_u64 v[250:251], v[248:249], 0, v[110:111]
	global_load_dwordx4 v[240:243], v[250:251], off
	v_lshl_add_u64 v[250:251], v[248:249], 0, v[112:113]
	global_load_dwordx4 v[244:247], v[250:251], off
	s_waitcnt lgkmcnt(0)
	s_barrier
	ds_read_b64_tr_b16 v[148:149], v129
	ds_read_b64_tr_b16 v[150:151], v129 offset:256
	ds_read_b128 v[164:167], v130
	ds_read_b128 v[168:171], v130 offset:8192
	ds_read_b128 v[172:175], v130 offset:16384
	ds_read_b128 v[184:187], v130 offset:24576
	ds_read_b64_tr_b16 v[152:153], v131
	ds_read_b64_tr_b16 v[154:155], v131 offset:256
	ds_read_b128 v[188:191], v132
	ds_read_b128 v[192:195], v132 offset:8192
	ds_read_b128 v[196:199], v132 offset:16384
	ds_read_b128 v[200:203], v132 offset:24576
	s_waitcnt lgkmcnt(9)
	v_mfma_f32_32x32x16_bf16 v[50:65], v[148:151], v[164:167], 0
	s_waitcnt lgkmcnt(8)
	v_mfma_f32_32x32x16_bf16 v[34:49], v[148:151], v[168:171], 0
	s_waitcnt lgkmcnt(7)
	v_mfma_f32_32x32x16_bf16 v[18:33], v[148:151], v[172:175], 0
	s_waitcnt lgkmcnt(6)
	v_mfma_f32_32x32x16_bf16 v[2:17], v[148:151], v[184:187], 0
	ds_read_b64_tr_b16 v[148:149], v133
	ds_read_b64_tr_b16 v[150:151], v133 offset:256
	ds_read_b128 v[164:167], v134
	ds_read_b128 v[168:171], v134 offset:8192
	ds_read_b128 v[172:175], v134 offset:16384
	ds_read_b128 v[184:187], v134 offset:24576
	s_waitcnt lgkmcnt(9)
	v_mfma_f32_32x32x16_bf16 v[50:65], v[152:155], v[188:191], v[50:65]
	s_waitcnt lgkmcnt(8)
	v_mfma_f32_32x32x16_bf16 v[34:49], v[152:155], v[192:195], v[34:49]
	s_waitcnt lgkmcnt(7)
	v_mfma_f32_32x32x16_bf16 v[18:33], v[152:155], v[196:199], v[18:33]
	s_waitcnt lgkmcnt(6)
	v_mfma_f32_32x32x16_bf16 v[2:17], v[152:155], v[200:203], v[2:17]
	ds_read_b64_tr_b16 v[152:153], v135
	ds_read_b64_tr_b16 v[154:155], v135 offset:256
	ds_read_b128 v[188:191], v136
	ds_read_b128 v[192:195], v136 offset:8192
	ds_read_b128 v[196:199], v136 offset:16384
	ds_read_b128 v[200:203], v136 offset:24576
	s_waitcnt lgkmcnt(9)
	v_mfma_f32_32x32x16_bf16 v[50:65], v[148:151], v[164:167], v[50:65]
	s_waitcnt lgkmcnt(8)
	v_mfma_f32_32x32x16_bf16 v[34:49], v[148:151], v[168:171], v[34:49]
	s_waitcnt lgkmcnt(7)
	v_mfma_f32_32x32x16_bf16 v[18:33], v[148:151], v[172:175], v[18:33]
	s_waitcnt lgkmcnt(6)
	v_mfma_f32_32x32x16_bf16 v[2:17], v[148:151], v[184:187], v[2:17]
	ds_read_b64_tr_b16 v[148:149], v137
	ds_read_b64_tr_b16 v[150:151], v137 offset:256
	ds_read_b128 v[164:167], v138
	ds_read_b128 v[168:171], v138 offset:8192
	ds_read_b128 v[172:175], v138 offset:16384
	ds_read_b128 v[184:187], v138 offset:24576
	s_waitcnt lgkmcnt(9)
	v_mfma_f32_32x32x16_bf16 v[50:65], v[152:155], v[188:191], v[50:65]
	s_waitcnt lgkmcnt(8)
	v_mfma_f32_32x32x16_bf16 v[34:49], v[152:155], v[192:195], v[34:49]
	s_waitcnt lgkmcnt(7)
; #define LAS __attribute__((address_space(3)))
; __device__ __forceinline__ unsigned cvt_pk_bf16(float lo, float hi) { f32x2 v = {lo, hi}; bf16x2_t b = __builtin_convertvector(v, bf16x2_t); return __builtin_bit_cast(unsigned, b); }
; __device__ __forceinline__ void phase_spatial(const Args& a, LAS unsigned char* lds, int j, int nchunks) {
;     ...
;         for (int pb = 0; pb < 4; ++pb)
; #pragma unroll
;             for (int i = 0; i < 16; ++i) acc[pb][i] = 0.f;
;         const int vb = wid * 8192 + ((lane >> 4) & 1) * 32 + (lane & 3) * 8 + ((lane & 15) >> 2) * 64;
; #pragma unroll
;         for (int ks = 0; ks < 8; ++ks) {
;             const s16x4 lo = __builtin_bit_cast(s16x4, __builtin_amdgcn_ds_read_tr16_b64_v4i16((LAS s16x4*)(vt + vb + (2 * ks + hi) * 512)));
;             const s16x4 hh = __builtin_bit_cast(s16x4, __builtin_amdgcn_ds_read_tr16_b64_v4i16((LAS s16x4*)(vt + vb + (2 * ks + hi) * 512 + 256)));
;             const bf16x8 vf = __builtin_shufflevector(lo, hh, 0, 1, 2, 3, 4, 5, 6, 7);
; #pragma unroll
;             for (int pb = 0; pb < 4; ++pb) { const int row = 32 * pb + r32; const bf16x8 wf = *(const LAS bf16x8*)(wl + row * 256 + (((2 * ks + hi) ^ (row & 15)) << 4));
;                 acc[pb] = __builtin_amdgcn_mfma_f32_32x32x16_bf16(vf, wf, acc[pb], 0, 0, 0); }
;         }
;         __syncthreads();
; #pragma unroll
;         for (int pb = 0; pb < 4; ++pb) { const int p = 32 * pb + r32; const float bias = bs[g * 128 + p];
; #pragma unroll
;             for (int g4 = 0; g4 < 4; ++g4) { u32x2 w; w.x = cvt_pk_bf16(acc[pb][4 * g4] + bias, acc[pb][4 * g4 + 1] + bias); w.y = cvt_pk_bf16(acc[pb][4 * g4 + 2] + bias, acc[pb][4 * g4 + 3] + bias);
;                 *(LAS u32x2*)(vt + p * 520 + (32 * wid + 8 * g4 + 4 * hi) * 2) = w; } }
;         __syncthreads();
	v_mfma_f32_32x32x16_bf16 v[18:33], v[152:155], v[196:199], v[18:33]
	s_waitcnt lgkmcnt(6)
	v_mfma_f32_32x32x16_bf16 v[2:17], v[152:155], v[200:203], v[2:17]
	ds_read_b64_tr_b16 v[152:153], v139
	ds_read_b64_tr_b16 v[154:155], v139 offset:256
	ds_read_b128 v[188:191], v140
	ds_read_b128 v[192:195], v140 offset:8192
	ds_read_b128 v[196:199], v140 offset:16384
	ds_read_b128 v[200:203], v140 offset:24576
	s_waitcnt lgkmcnt(9)
	v_mfma_f32_32x32x16_bf16 v[50:65], v[148:151], v[164:167], v[50:65]
	s_waitcnt lgkmcnt(8)
	v_mfma_f32_32x32x16_bf16 v[34:49], v[148:151], v[168:171], v[34:49]
	s_waitcnt lgkmcnt(7)
	v_mfma_f32_32x32x16_bf16 v[18:33], v[148:151], v[172:175], v[18:33]
	s_waitcnt lgkmcnt(6)
	v_mfma_f32_32x32x16_bf16 v[2:17], v[148:151], v[184:187], v[2:17]
	ds_read_b64_tr_b16 v[148:149], v141
	ds_read_b64_tr_b16 v[150:151], v141 offset:256
	ds_read_b128 v[164:167], v142
	ds_read_b128 v[168:171], v142 offset:8192
	ds_read_b128 v[172:175], v142 offset:16384
	ds_read_b128 v[184:187], v142 offset:24576
	s_waitcnt lgkmcnt(9)
	v_mfma_f32_32x32x16_bf16 v[50:65], v[152:155], v[188:191], v[50:65]
	s_waitcnt lgkmcnt(8)
	v_mfma_f32_32x32x16_bf16 v[34:49], v[152:155], v[192:195], v[34:49]
	s_waitcnt lgkmcnt(7)
	v_mfma_f32_32x32x16_bf16 v[18:33], v[152:155], v[196:199], v[18:33]
	s_waitcnt lgkmcnt(6)
	v_mfma_f32_32x32x16_bf16 v[2:17], v[152:155], v[200:203], v[2:17]
	ds_read_b64_tr_b16 v[152:153], v143
	ds_read_b64_tr_b16 v[154:155], v143 offset:256
	ds_read_b128 v[188:191], v144
	ds_read_b128 v[192:195], v144 offset:8192
	ds_read_b128 v[196:199], v144 offset:16384
	ds_read_b128 v[200:203], v144 offset:24576
	s_waitcnt lgkmcnt(9)
	v_mfma_f32_32x32x16_bf16 v[50:65], v[148:151], v[164:167], v[50:65]
	s_waitcnt lgkmcnt(8)
	v_mfma_f32_32x32x16_bf16 v[34:49], v[148:151], v[168:171], v[34:49]
	s_waitcnt lgkmcnt(7)
	v_mfma_f32_32x32x16_bf16 v[18:33], v[148:151], v[172:175], v[18:33]
	s_waitcnt lgkmcnt(6)
	v_mfma_f32_32x32x16_bf16 v[2:17], v[148:151], v[184:187], v[2:17]
	s_waitcnt lgkmcnt(3)
	v_mfma_f32_32x32x16_bf16 v[50:65], v[152:155], v[188:191], v[50:65]
	s_waitcnt lgkmcnt(2)
	v_mfma_f32_32x32x16_bf16 v[34:49], v[152:155], v[192:195], v[34:49]
	s_waitcnt lgkmcnt(1)
	v_mfma_f32_32x32x16_bf16 v[18:33], v[152:155], v[196:199], v[18:33]
	s_waitcnt lgkmcnt(0)
	s_barrier
	v_mfma_f32_32x32x16_bf16 v[2:17], v[152:155], v[200:203], v[2:17]
	s_nop 4
	s_waitcnt vmcnt(0)
	v_mov_b32_e32 v148, v224
	s_waitcnt vmcnt(0)
	v_add_f32_e64 v50, v50, v148
	v_add_f32_e64 v51, v51, v148
	v_add_f32_e64 v52, v52, v148
	v_add_f32_e64 v53, v53, v148
	v_cvt_pk_bf16_f32 v50, v50, v51
	v_cvt_pk_bf16_f32 v51, v52, v53
	v_pk_add_f32 v[52:53], v[54:55], v[148:149] op_sel_hi:[1,0]
	v_pk_add_f32 v[54:55], v[56:57], v[148:149] op_sel_hi:[1,0]
	v_cvt_pk_bf16_f32 v52, v52, v53
	v_cvt_pk_bf16_f32 v53, v54, v55
	ds_write2_b64 v145, v[50:51], v[52:53] offset1:2
	v_pk_add_f32 v[50:51], v[58:59], v[148:149] op_sel_hi:[1,0]
	v_pk_add_f32 v[52:53], v[60:61], v[148:149] op_sel_hi:[1,0]
	v_cvt_pk_bf16_f32 v50, v50, v51
	v_cvt_pk_bf16_f32 v51, v52, v53
	v_pk_add_f32 v[52:53], v[62:63], v[148:149] op_sel_hi:[1,0]
	v_pk_add_f32 v[54:55], v[64:65], v[148:149] op_sel_hi:[1,0]
	v_cvt_pk_bf16_f32 v52, v52, v53
	v_cvt_pk_bf16_f32 v53, v54, v55
	ds_write2_b64 v145, v[50:51], v[52:53] offset0:4 offset1:6
	s_waitcnt vmcnt(0)
	v_mov_b32_e32 v50, v225
	s_waitcnt vmcnt(0)
	v_pk_add_f32 v[34:35], v[34:35], v[50:51] op_sel_hi:[1,0]
	v_pk_add_f32 v[36:37], v[36:37], v[50:51] op_sel_hi:[1,0]
	v_cvt_pk_bf16_f32 v34, v34, v35
	v_cvt_pk_bf16_f32 v35, v36, v37
	v_pk_add_f32 v[36:37], v[38:39], v[50:51] op_sel_hi:[1,0]
	v_pk_add_f32 v[38:39], v[40:41], v[50:51] op_sel_hi:[1,0]
	v_cvt_pk_bf16_f32 v36, v36, v37
	v_cvt_pk_bf16_f32 v37, v38, v39
	v_add_u32_e32 v40, 0x4000, v145
	ds_write2_b64 v40, v[34:35], v[36:37] offset0:32 offset1:34
	v_pk_add_f32 v[34:35], v[42:43], v[50:51] op_sel_hi:[1,0]
	v_pk_add_f32 v[36:37], v[44:45], v[50:51] op_sel_hi:[1,0]
	v_cvt_pk_bf16_f32 v34, v34, v35
	v_cvt_pk_bf16_f32 v35, v36, v37
	v_pk_add_f32 v[36:37], v[46:47], v[50:51] op_sel_hi:[1,0]
	v_pk_add_f32 v[38:39], v[48:49], v[50:51] op_sel_hi:[1,0]
	v_cvt_pk_bf16_f32 v36, v36, v37
	v_cvt_pk_bf16_f32 v37, v38, v39
	ds_write2_b64 v40, v[34:35], v[36:37] offset0:36 offset1:38
	s_waitcnt vmcnt(0)
	v_mov_b32_e32 v34, v226
	v_add_u32_e32 v48, v115, v116
	s_waitcnt vmcnt(0)
	v_pk_add_f32 v[18:19], v[18:19], v[34:35] op_sel_hi:[1,0]
	v_pk_add_f32 v[20:21], v[20:21], v[34:35] op_sel_hi:[1,0]
	v_cvt_pk_bf16_f32 v18, v18, v19
	v_cvt_pk_bf16_f32 v19, v20, v21
	v_pk_add_f32 v[20:21], v[22:23], v[34:35] op_sel_hi:[1,0]
	v_pk_add_f32 v[22:23], v[24:25], v[34:35] op_sel_hi:[1,0]
	v_cvt_pk_bf16_f32 v20, v20, v21
	v_cvt_pk_bf16_f32 v21, v22, v23
	v_add_u32_e32 v24, 0x8000, v145
	ds_write2_b64 v24, v[18:19], v[20:21] offset0:64 offset1:66
	v_pk_add_f32 v[18:19], v[26:27], v[34:35] op_sel_hi:[1,0]
	v_pk_add_f32 v[20:21], v[28:29], v[34:35] op_sel_hi:[1,0]
	v_cvt_pk_bf16_f32 v18, v18, v19
	v_cvt_pk_bf16_f32 v19, v20, v21
	v_pk_add_f32 v[20:21], v[30:31], v[34:35] op_sel_hi:[1,0]
	v_pk_add_f32 v[22:23], v[32:33], v[34:35] op_sel_hi:[1,0]
	v_cvt_pk_bf16_f32 v20, v20, v21
	v_cvt_pk_bf16_f32 v21, v22, v23
	ds_write2_b64 v24, v[18:19], v[20:21] offset0:68 offset1:70
	s_waitcnt vmcnt(0)
	v_mov_b32_e32 v18, v227
	s_waitcnt vmcnt(0)
	v_pk_add_f32 v[2:3], v[2:3], v[18:19] op_sel_hi:[1,0]
	v_pk_add_f32 v[4:5], v[4:5], v[18:19] op_sel_hi:[1,0]
	v_cvt_pk_bf16_f32 v2, v2, v3
	v_cvt_pk_bf16_f32 v3, v4, v5
	v_pk_add_f32 v[4:5], v[6:7], v[18:19] op_sel_hi:[1,0]
	v_pk_add_f32 v[6:7], v[8:9], v[18:19] op_sel_hi:[1,0]
	v_cvt_pk_bf16_f32 v4, v4, v5
	v_cvt_pk_bf16_f32 v5, v6, v7
	v_add_u32_e32 v8, 0xc000, v145
	ds_write2_b64 v8, v[2:3], v[4:5] offset0:96 offset1:98
	v_pk_add_f32 v[2:3], v[10:11], v[18:19] op_sel_hi:[1,0]
	v_pk_add_f32 v[4:5], v[12:13], v[18:19] op_sel_hi:[1,0]
	v_cvt_pk_bf16_f32 v2, v2, v3
	v_cvt_pk_bf16_f32 v3, v4, v5
	v_pk_add_f32 v[4:5], v[14:15], v[18:19] op_sel_hi:[1,0]
	v_pk_add_f32 v[6:7], v[16:17], v[18:19] op_sel_hi:[1,0]
	v_cvt_pk_bf16_f32 v4, v4, v5
	v_cvt_pk_bf16_f32 v5, v6, v7
	ds_write2_b64 v8, v[2:3], v[4:5] offset0:100 offset1:102
	v_lshl_add_u64 v[2:3], v[74:75], 0, s[0:1]
	v_lshl_add_u64 v[52:53], v[2:3], 0, v[98:99]
	s_waitcnt lgkmcnt(0)
	s_barrier
; #define LAS __attribute__((address_space(3)))
; __device__ __forceinline__ unsigned cvt_pk_bf16(float lo, float hi) { f32x2 v = {lo, hi}; bf16x2_t b = __builtin_convertvector(v, bf16x2_t); return __builtin_bit_cast(unsigned, b); }
; __device__ __forceinline__ float bf_lo(unsigned u) { return __uint_as_float(u << 16); }
; __device__ __forceinline__ float bf_hi(unsigned u) { return __uint_as_float(u & 0xffff0000u); }
; __device__ __forceinline__ void phase_spatial(const Args& a, LAS unsigned char* lds, int j, int nchunks) {
;     ...
;         { u32x4 uu[8];
; #pragma unroll
;           for (int p8 = 0; p8 < 8; ++p8) { const int row = lrow + 16 * p8; uu[p8] = *(const u32x4*)(Z + (row0 + row) * SGUW + g * 256 + lch * 8); }
; #pragma unroll
;           for (int p8 = 0; p8 < 8; ++p8) { const int row = lrow + 16 * p8; const u32x2 s0 = *(const LAS u32x2*)(vt + row * 520 + lch * 16), s1 = *(const LAS u32x2*)(vt + row * 520 + lch * 16 + 8);
;               u32x4 o; o.x = cvt_pk_bf16(bf_lo(uu[p8].x) * bf_lo(s0.x), bf_hi(uu[p8].x) * bf_hi(s0.x)); o.y = cvt_pk_bf16(bf_lo(uu[p8].y) * bf_lo(s0.y), bf_hi(uu[p8].y) * bf_hi(s0.y));
;               o.z = cvt_pk_bf16(bf_lo(uu[p8].z) * bf_lo(s1.x), bf_hi(uu[p8].z) * bf_hi(s1.x)); o.w = cvt_pk_bf16(bf_lo(uu[p8].w) * bf_lo(s1.y), bf_hi(uu[p8].w) * bf_hi(s1.y));
;               *(u32x4*)(Z + (row0 + row) * SGUW + g * 256 + lch * 8) = o; } }
	s_waitcnt vmcnt(0)
	v_mov_b64_e32 v[44:45], v[156:157]
	v_mov_b64_e32 v[46:47], v[158:159]
	v_lshl_add_u64 v[42:43], v[2:3], 0, v[100:101]
	v_mov_b64_e32 v[26:27], v[160:161]
	v_mov_b64_e32 v[28:29], v[162:163]
	v_lshl_add_u64 v[40:41], v[2:3], 0, v[102:103]
	v_mov_b64_e32 v[22:23], v[208:209]
	v_mov_b64_e32 v[24:25], v[210:211]
	v_lshl_add_u64 v[38:39], v[2:3], 0, v[104:105]
	v_mov_b64_e32 v[18:19], v[228:229]
	v_mov_b64_e32 v[20:21], v[230:231]
	v_lshl_add_u64 v[36:37], v[2:3], 0, v[106:107]
	v_mov_b64_e32 v[14:15], v[232:233]
	v_mov_b64_e32 v[16:17], v[234:235]
	v_lshl_add_u64 v[34:35], v[2:3], 0, v[108:109]
	v_mov_b64_e32 v[10:11], v[236:237]
	v_mov_b64_e32 v[12:13], v[238:239]
	ds_read2_b64 v[48:51], v48 offset1:1
	v_lshl_add_u64 v[32:33], v[2:3], 0, v[110:111]
	v_mov_b64_e32 v[6:7], v[240:241]
	v_mov_b64_e32 v[8:9], v[242:243]
	v_lshl_add_u64 v[30:31], v[2:3], 0, v[112:113]
	v_mov_b64_e32 v[2:3], v[244:245]
	v_mov_b64_e32 v[4:5], v[246:247]
	s_waitcnt lgkmcnt(0)
	v_lshlrev_b32_e32 v56, 16, v48
	v_and_b32_e32 v57, 0xffff0000, v48
	v_lshlrev_b32_e32 v48, 16, v49
	v_and_b32_e32 v49, 0xffff0000, v49
	s_waitcnt vmcnt(7)
	v_lshlrev_b32_e32 v54, 16, v44
	v_and_b32_e32 v55, 0xffff0000, v44
	v_pk_mul_f32 v[54:55], v[54:55], v[56:57]
	s_nop 0
	v_cvt_pk_bf16_f32 v44, v54, v55
	v_lshlrev_b32_e32 v54, 16, v45
	v_and_b32_e32 v55, 0xffff0000, v45
	v_pk_mul_f32 v[48:49], v[54:55], v[48:49]
	v_lshlrev_b32_e32 v54, 16, v50
	v_cvt_pk_bf16_f32 v45, v48, v49
	v_lshlrev_b32_e32 v48, 16, v46
	v_and_b32_e32 v49, 0xffff0000, v46
	v_and_b32_e32 v55, 0xffff0000, v50
	v_pk_mul_f32 v[48:49], v[48:49], v[54:55]
	v_lshlrev_b32_e32 v50, 16, v51
	v_cvt_pk_bf16_f32 v46, v48, v49
	v_lshlrev_b32_e32 v48, 16, v47
	v_and_b32_e32 v49, 0xffff0000, v47
	v_and_b32_e32 v51, 0xffff0000, v51
	v_pk_mul_f32 v[48:49], v[48:49], v[50:51]
	s_nop 0
	v_cvt_pk_bf16_f32 v47, v48, v49
	global_store_dwordx4 v[52:53], v[44:47], off
	ds_read2_b64 v[44:47], v146 offset1:1
	s_waitcnt vmcnt(7)
	v_lshlrev_b32_e32 v48, 16, v26
	v_and_b32_e32 v49, 0xffff0000, v26
	s_waitcnt lgkmcnt(0)
	v_lshlrev_b32_e32 v50, 16, v44
	v_and_b32_e32 v51, 0xffff0000, v44
	v_pk_mul_f32 v[48:49], v[48:49], v[50:51]
	v_lshlrev_b32_e32 v44, 16, v45
	v_cvt_pk_bf16_f32 v26, v48, v49
	v_lshlrev_b32_e32 v48, 16, v27
	v_and_b32_e32 v49, 0xffff0000, v27
	v_and_b32_e32 v45, 0xffff0000, v45
	v_pk_mul_f32 v[44:45], v[48:49], v[44:45]
	v_lshlrev_b32_e32 v48, 16, v46
	v_cvt_pk_bf16_f32 v27, v44, v45
	v_lshlrev_b32_e32 v44, 16, v28
	v_and_b32_e32 v45, 0xffff0000, v28
	v_and_b32_e32 v49, 0xffff0000, v46
	v_pk_mul_f32 v[44:45], v[44:45], v[48:49]
	v_lshlrev_b32_e32 v46, 16, v47
	v_cvt_pk_bf16_f32 v28, v44, v45
	v_lshlrev_b32_e32 v44, 16, v29
	v_and_b32_e32 v45, 0xffff0000, v29
	v_and_b32_e32 v47, 0xffff0000, v47
	v_pk_mul_f32 v[44:45], v[44:45], v[46:47]
	s_nop 0
	v_cvt_pk_bf16_f32 v29, v44, v45
	global_store_dwordx4 v[42:43], v[26:29], off
	s_waitcnt vmcnt(7)
	v_lshlrev_b32_e32 v42, 16, v22
	v_and_b32_e32 v43, 0xffff0000, v22
	v_add_u32_e32 v26, 0x2080, v146
	ds_read2_b64 v[26:29], v26 offset1:1
	s_waitcnt lgkmcnt(0)
	v_lshlrev_b32_e32 v44, 16, v26
	v_and_b32_e32 v45, 0xffff0000, v26
	v_pk_mul_f32 v[42:43], v[42:43], v[44:45]
	v_lshlrev_b32_e32 v26, 16, v27
	v_cvt_pk_bf16_f32 v22, v42, v43
	v_lshlrev_b32_e32 v42, 16, v23
	v_and_b32_e32 v43, 0xffff0000, v23
	v_and_b32_e32 v27, 0xffff0000, v27
	v_pk_mul_f32 v[26:27], v[42:43], v[26:27]
	v_lshlrev_b32_e32 v42, 16, v28
	v_cvt_pk_bf16_f32 v23, v26, v27
	v_lshlrev_b32_e32 v26, 16, v24
	v_and_b32_e32 v27, 0xffff0000, v24
	v_and_b32_e32 v43, 0xffff0000, v28
	v_pk_mul_f32 v[26:27], v[26:27], v[42:43]
	v_lshlrev_b32_e32 v28, 16, v29
	v_cvt_pk_bf16_f32 v24, v26, v27
	v_lshlrev_b32_e32 v26, 16, v25
	v_and_b32_e32 v27, 0xffff0000, v25
	v_and_b32_e32 v29, 0xffff0000, v29
	v_pk_mul_f32 v[26:27], v[26:27], v[28:29]
	s_nop 0
	v_cvt_pk_bf16_f32 v25, v26, v27
	global_store_dwordx4 v[40:41], v[22:25], off
	s_waitcnt vmcnt(7)
	v_lshlrev_b32_e32 v26, 16, v18
	v_and_b32_e32 v27, 0xffff0000, v18
	v_add_u32_e32 v22, 0x4100, v146
	ds_read2_b64 v[22:25], v22 offset1:1
	s_waitcnt lgkmcnt(0)
; #define LAS __attribute__((address_space(3)))
; __device__ __forceinline__ unsigned cvt_pk_bf16(float lo, float hi) { f32x2 v = {lo, hi}; bf16x2_t b = __builtin_convertvector(v, bf16x2_t); return __builtin_bit_cast(unsigned, b); }
; __device__ __forceinline__ float bf_lo(unsigned u) { return __uint_as_float(u << 16); }
; __device__ __forceinline__ float bf_hi(unsigned u) { return __uint_as_float(u & 0xffff0000u); }
; __device__ __forceinline__ void phase_spatial(const Args& a, LAS unsigned char* lds, int j, int nchunks) {
;     ...
;         { u32x4 uu[8];
; #pragma unroll
;           for (int p8 = 0; p8 < 8; ++p8) { const int row = lrow + 16 * p8; uu[p8] = *(const u32x4*)(Z + (row0 + row) * SGUW + g * 256 + lch * 8); }
; #pragma unroll
;           for (int p8 = 0; p8 < 8; ++p8) { const int row = lrow + 16 * p8; const u32x2 s0 = *(const LAS u32x2*)(vt + row * 520 + lch * 16), s1 = *(const LAS u32x2*)(vt + row * 520 + lch * 16 + 8);
;               u32x4 o; o.x = cvt_pk_bf16(bf_lo(uu[p8].x) * bf_lo(s0.x), bf_hi(uu[p8].x) * bf_hi(s0.x)); o.y = cvt_pk_bf16(bf_lo(uu[p8].y) * bf_lo(s0.y), bf_hi(uu[p8].y) * bf_hi(s0.y));
;               o.z = cvt_pk_bf16(bf_lo(uu[p8].z) * bf_lo(s1.x), bf_hi(uu[p8].z) * bf_hi(s1.x)); o.w = cvt_pk_bf16(bf_lo(uu[p8].w) * bf_lo(s1.y), bf_hi(uu[p8].w) * bf_hi(s1.y));
;               *(u32x4*)(Z + (row0 + row) * SGUW + g * 256 + lch * 8) = o; } }
;         __syncthreads();
	v_lshlrev_b32_e32 v28, 16, v22
	v_and_b32_e32 v29, 0xffff0000, v22
	v_pk_mul_f32 v[26:27], v[26:27], v[28:29]
	v_lshlrev_b32_e32 v22, 16, v23
	v_cvt_pk_bf16_f32 v18, v26, v27
	v_lshlrev_b32_e32 v26, 16, v19
	v_and_b32_e32 v27, 0xffff0000, v19
	v_and_b32_e32 v23, 0xffff0000, v23
	v_pk_mul_f32 v[22:23], v[26:27], v[22:23]
	v_lshlrev_b32_e32 v26, 16, v24
	v_cvt_pk_bf16_f32 v19, v22, v23
	v_lshlrev_b32_e32 v22, 16, v20
	v_and_b32_e32 v23, 0xffff0000, v20
	v_and_b32_e32 v27, 0xffff0000, v24
	v_pk_mul_f32 v[22:23], v[22:23], v[26:27]
	v_lshlrev_b32_e32 v24, 16, v25
	v_cvt_pk_bf16_f32 v20, v22, v23
	v_lshlrev_b32_e32 v22, 16, v21
	v_and_b32_e32 v23, 0xffff0000, v21
	v_and_b32_e32 v25, 0xffff0000, v25
	v_pk_mul_f32 v[22:23], v[22:23], v[24:25]
	s_nop 0
	v_cvt_pk_bf16_f32 v21, v22, v23
	global_store_dwordx4 v[38:39], v[18:21], off
	s_waitcnt vmcnt(7)
	v_lshlrev_b32_e32 v22, 16, v14
	v_and_b32_e32 v23, 0xffff0000, v14
	v_add_u32_e32 v18, 0x6180, v146
	ds_read2_b64 v[18:21], v18 offset1:1
	s_waitcnt lgkmcnt(0)
	v_lshlrev_b32_e32 v24, 16, v18
	v_and_b32_e32 v25, 0xffff0000, v18
	v_pk_mul_f32 v[22:23], v[22:23], v[24:25]
	v_lshlrev_b32_e32 v18, 16, v19
	v_cvt_pk_bf16_f32 v14, v22, v23
	v_lshlrev_b32_e32 v22, 16, v15
	v_and_b32_e32 v23, 0xffff0000, v15
	v_and_b32_e32 v19, 0xffff0000, v19
	v_pk_mul_f32 v[18:19], v[22:23], v[18:19]
	v_lshlrev_b32_e32 v22, 16, v20
	v_cvt_pk_bf16_f32 v15, v18, v19
	v_lshlrev_b32_e32 v18, 16, v16
	v_and_b32_e32 v19, 0xffff0000, v16
	v_and_b32_e32 v23, 0xffff0000, v20
	v_pk_mul_f32 v[18:19], v[18:19], v[22:23]
	v_lshlrev_b32_e32 v20, 16, v21
	v_cvt_pk_bf16_f32 v16, v18, v19
	v_lshlrev_b32_e32 v18, 16, v17
	v_and_b32_e32 v19, 0xffff0000, v17
	v_and_b32_e32 v21, 0xffff0000, v21
	v_pk_mul_f32 v[18:19], v[18:19], v[20:21]
	s_nop 0
	v_cvt_pk_bf16_f32 v17, v18, v19
	global_store_dwordx4 v[36:37], v[14:17], off
	s_waitcnt vmcnt(7)
	v_lshlrev_b32_e32 v18, 16, v10
	v_and_b32_e32 v19, 0xffff0000, v10
	v_add_u32_e32 v14, 0x8200, v146
	ds_read2_b64 v[14:17], v14 offset1:1
	s_waitcnt lgkmcnt(0)
	v_lshlrev_b32_e32 v20, 16, v14
	v_and_b32_e32 v21, 0xffff0000, v14
	v_pk_mul_f32 v[18:19], v[18:19], v[20:21]
	v_lshlrev_b32_e32 v14, 16, v15
	v_cvt_pk_bf16_f32 v10, v18, v19
	v_lshlrev_b32_e32 v18, 16, v11
	v_and_b32_e32 v19, 0xffff0000, v11
	v_and_b32_e32 v15, 0xffff0000, v15
	v_pk_mul_f32 v[14:15], v[18:19], v[14:15]
	v_lshlrev_b32_e32 v18, 16, v16
	v_cvt_pk_bf16_f32 v11, v14, v15
	v_lshlrev_b32_e32 v14, 16, v12
	v_and_b32_e32 v15, 0xffff0000, v12
	v_and_b32_e32 v19, 0xffff0000, v16
	v_pk_mul_f32 v[14:15], v[14:15], v[18:19]
	v_lshlrev_b32_e32 v16, 16, v17
	v_cvt_pk_bf16_f32 v12, v14, v15
	v_lshlrev_b32_e32 v14, 16, v13
	v_and_b32_e32 v15, 0xffff0000, v13
	v_and_b32_e32 v17, 0xffff0000, v17
	v_pk_mul_f32 v[14:15], v[14:15], v[16:17]
	s_nop 0
	v_cvt_pk_bf16_f32 v13, v14, v15
	global_store_dwordx4 v[34:35], v[10:13], off
	s_waitcnt vmcnt(7)
	v_lshlrev_b32_e32 v14, 16, v6
	v_and_b32_e32 v15, 0xffff0000, v6
	v_add_u32_e32 v10, 0xa280, v146
	ds_read2_b64 v[10:13], v10 offset1:1
	s_waitcnt lgkmcnt(0)
	v_lshlrev_b32_e32 v16, 16, v10
	v_and_b32_e32 v17, 0xffff0000, v10
	v_pk_mul_f32 v[14:15], v[14:15], v[16:17]
	v_lshlrev_b32_e32 v10, 16, v11
	v_cvt_pk_bf16_f32 v6, v14, v15
	v_lshlrev_b32_e32 v14, 16, v7
	v_and_b32_e32 v15, 0xffff0000, v7
	v_and_b32_e32 v11, 0xffff0000, v11
	v_pk_mul_f32 v[10:11], v[14:15], v[10:11]
	v_lshlrev_b32_e32 v14, 16, v12
	v_cvt_pk_bf16_f32 v7, v10, v11
	v_lshlrev_b32_e32 v10, 16, v8
	v_and_b32_e32 v11, 0xffff0000, v8
	v_and_b32_e32 v15, 0xffff0000, v12
	v_pk_mul_f32 v[10:11], v[10:11], v[14:15]
	v_lshlrev_b32_e32 v12, 16, v13
	v_cvt_pk_bf16_f32 v8, v10, v11
	v_lshlrev_b32_e32 v10, 16, v9
	v_and_b32_e32 v11, 0xffff0000, v9
	v_and_b32_e32 v13, 0xffff0000, v13
	v_pk_mul_f32 v[10:11], v[10:11], v[12:13]
	s_nop 0
	v_cvt_pk_bf16_f32 v9, v10, v11
	global_store_dwordx4 v[32:33], v[6:9], off
	s_waitcnt vmcnt(7)
	v_lshlrev_b32_e32 v10, 16, v2
	v_and_b32_e32 v11, 0xffff0000, v2
	v_add_u32_e32 v6, 0xc300, v146
	ds_read2_b64 v[6:9], v6 offset1:1
	s_waitcnt lgkmcnt(0)
	v_lshlrev_b32_e32 v12, 16, v6
	v_and_b32_e32 v13, 0xffff0000, v6
	v_pk_mul_f32 v[10:11], v[10:11], v[12:13]
	v_lshlrev_b32_e32 v6, 16, v7
	v_cvt_pk_bf16_f32 v2, v10, v11
	v_lshlrev_b32_e32 v10, 16, v3
	v_and_b32_e32 v11, 0xffff0000, v3
	v_and_b32_e32 v7, 0xffff0000, v7
	v_pk_mul_f32 v[6:7], v[10:11], v[6:7]
	v_lshlrev_b32_e32 v10, 16, v8
	v_cvt_pk_bf16_f32 v3, v6, v7
	v_lshlrev_b32_e32 v6, 16, v4
	v_and_b32_e32 v7, 0xffff0000, v4
	v_and_b32_e32 v11, 0xffff0000, v8
	v_pk_mul_f32 v[6:7], v[6:7], v[10:11]
	v_lshlrev_b32_e32 v8, 16, v9
	v_cvt_pk_bf16_f32 v4, v6, v7
	v_lshlrev_b32_e32 v6, 16, v5
	v_and_b32_e32 v7, 0xffff0000, v5
	v_and_b32_e32 v9, 0xffff0000, v9
	v_pk_mul_f32 v[6:7], v[6:7], v[8:9]
	s_nop 0
	v_cvt_pk_bf16_f32 v5, v6, v7
	global_store_dwordx4 v[30:31], v[2:5], off
	s_barrier
	s_cbranch_scc1 .LBB0_254
